# attention finalize: lanes q and q+32 exchange halves (permlane32 swap) so each lane stores 64 contiguous bytes: 4 dwordx4 stores instead of 16 dword stores
# baseline (speedup 1.0000x reference)
.LBB0_447:
	s_or_b64 exec, exec, s[0:1]
	s_mov_b64 s[0:1], s[86:87]
	s_waitcnt lgkmcnt(0)
	s_barrier
	s_load_dwordx2 s[0:1], s[86:87], 0xa8
	s_mov_b32 s15, m0
	v_and_b32_e32 v1, 63, v0
	v_and_b32_e32 v2, 31, v0
	v_bfe_u32 v3, v0, 5, 1
	v_readfirstlane_b32 s18, v0
	v_mov_b32_e32 v15, 0x7f7f7f7f
	s_nop 3
	s_lshr_b32 s18, s18, 6
	s_lshl_b32 s14, s18, 10
	v_lshrrev_b32_e32 v13, 2, v1
	s_and_b32 s19, s18, 3
	s_lshl_b32 s19, s19, 4
	v_add_u32_e32 v13, s19, v13
	v_mul_u32_u24_e32 v4, 0xc0, v13
	v_lshrrev_b32_e32 v14, 4, v1
	v_xor_b32_e32 v14, v14, v1
	v_and_b32_e32 v14, 3, v14
	v_lshlrev_b32_e32 v14, 4, v14
	s_lshr_b32 s20, s18, 2
	s_lshl_b32 s20, s20, 6
	v_add3_u32 v4, v4, v14, s20
	v_add_u32_e32 v247, 0x40, v4
	v_add_u32_e32 v5, 0x80, v4
	v_lshrrev_b32_e32 v13, 2, v1
	s_lshl_b32 s19, s18, 4
	v_add_u32_e32 v13, s19, v13
	v_mul_u32_u24_e32 v13, 0x2000, v13
	v_add_u32_e32 v6, v13, v14
	v_bfe_u32 v13, v2, 2, 1
	v_lshlrev_b32_e32 v13, 5, v13
	v_and_b32_e32 v14, 3, v2
	v_add_u32_e32 v13, v13, v14
	v_lshrrev_b32_e32 v14, 3, v2
	v_lshl_add_u32 v13, v14, 2, v13
	v_lshlrev_b32_e32 v13, 6, v13
	v_lshlrev_b32_e32 v246, 1, v3
	v_xor_b32_e32 v246, v246, v14
	v_lshl_add_u32 v7, v246, 4, v13
	v_xor_b32_e32 v8, 16, v7
	v_bfe_u32 v13, v2, 2, 2
	v_lshlrev_b32_e32 v14, 1, v3
	v_xor_b32_e32 v13, v13, v14
	v_lshlrev_b32_e32 v13, 4, v13
	v_lshl_add_u32 v9, v2, 6, v13
	v_add_u32_e32 v9, 0xc000, v9
	v_xor_b32_e32 v10, 16, v9
	s_lshl_b32 s19, s18, 5
	v_add_u32_e32 v13, s19, v2
	v_mul_u32_u24_e32 v240, 0xc00, v13
	v_lshl_add_u32 v240, v3, 5, v240
	v_lshlrev_b32_e32 v241, 11, v13
	v_lshl_add_u32 v241, v3, 6, v241
	s_mov_b32 s12, 0
	s_waitcnt lgkmcnt(0)

.Latt_final:
	s_nop 15
	s_nop 4
	v_rcp_f32_e32 v13, v11
	s_nop 0
	v_mul_f32_e32 v13, 0x42000000, v13
	v_mul_f32_e32 v64, v64, v13
	v_mul_f32_e32 v65, v65, v13
	v_mul_f32_e32 v66, v66, v13
	v_mul_f32_e32 v67, v67, v13
	v_mul_f32_e32 v68, v68, v13
	v_mul_f32_e32 v69, v69, v13
	v_mul_f32_e32 v70, v70, v13
	v_mul_f32_e32 v71, v71, v13
	v_mul_f32_e32 v72, v72, v13
	v_mul_f32_e32 v73, v73, v13
	v_mul_f32_e32 v74, v74, v13
	v_mul_f32_e32 v75, v75, v13
	v_mul_f32_e32 v76, v76, v13
	v_mul_f32_e32 v77, v77, v13
	v_mul_f32_e32 v78, v78, v13
	v_mul_f32_e32 v79, v79, v13
	v_mul_f32_e32 v80, v80, v13
	v_mul_f32_e32 v81, v81, v13
	v_mul_f32_e32 v82, v82, v13
	v_mul_f32_e32 v83, v83, v13
	v_mul_f32_e32 v84, v84, v13
	v_mul_f32_e32 v85, v85, v13
	v_mul_f32_e32 v86, v86, v13
	v_mul_f32_e32 v87, v87, v13
	v_mul_f32_e32 v88, v88, v13
	v_mul_f32_e32 v89, v89, v13
	v_mul_f32_e32 v90, v90, v13
	v_mul_f32_e32 v91, v91, v13
	v_mul_f32_e32 v92, v92, v13
	v_mul_f32_e32 v93, v93, v13
	v_mul_f32_e32 v94, v94, v13
	v_mul_f32_e32 v95, v95, v13
	v_mul_f32_e32 v96, v96, v13
	v_mul_f32_e32 v97, v97, v13
	v_mul_f32_e32 v98, v98, v13
	v_mul_f32_e32 v99, v99, v13
	v_mul_f32_e32 v100, v100, v13
	v_mul_f32_e32 v101, v101, v13
	v_mul_f32_e32 v102, v102, v13
	v_mul_f32_e32 v103, v103, v13
	v_mul_f32_e32 v104, v104, v13
	v_mul_f32_e32 v105, v105, v13
	v_mul_f32_e32 v106, v106, v13
	v_mul_f32_e32 v107, v107, v13
	v_mul_f32_e32 v108, v108, v13
	v_mul_f32_e32 v109, v109, v13
	v_mul_f32_e32 v110, v110, v13
	v_mul_f32_e32 v111, v111, v13
	v_mul_f32_e32 v112, v112, v13
	v_mul_f32_e32 v113, v113, v13
	v_mul_f32_e32 v114, v114, v13
	v_mul_f32_e32 v115, v115, v13
	v_mul_f32_e32 v116, v116, v13
	v_mul_f32_e32 v117, v117, v13
	v_mul_f32_e32 v118, v118, v13
	v_mul_f32_e32 v119, v119, v13
	v_mul_f32_e32 v120, v120, v13
	v_mul_f32_e32 v121, v121, v13
	v_mul_f32_e32 v122, v122, v13
	v_mul_f32_e32 v123, v123, v13
	v_mul_f32_e32 v124, v124, v13
	v_mul_f32_e32 v125, v125, v13
	v_mul_f32_e32 v126, v126, v13
	v_mul_f32_e32 v127, v127, v13
	v_cvt_pk_fp8_f32 v152, v64, v65
	v_cvt_pk_fp8_f32 v154, v68, v69
	v_cvt_pk_fp8_f32 v156, v72, v73
	v_cvt_pk_fp8_f32 v158, v76, v77
	v_cvt_pk_fp8_f32 v160, v80, v81
	v_cvt_pk_fp8_f32 v162, v84, v85
	v_cvt_pk_fp8_f32 v164, v88, v89
	v_cvt_pk_fp8_f32 v166, v92, v93
	v_cvt_pk_fp8_f32 v153, v96, v97
	v_cvt_pk_fp8_f32 v155, v100, v101
	v_cvt_pk_fp8_f32 v157, v104, v105
	v_cvt_pk_fp8_f32 v159, v108, v109
	v_cvt_pk_fp8_f32 v161, v112, v113
	v_cvt_pk_fp8_f32 v163, v116, v117
	v_cvt_pk_fp8_f32 v165, v120, v121
	v_cvt_pk_fp8_f32 v167, v124, v125
	v_cvt_pk_fp8_f32 v152, v66, v67 op_sel:[0,0,1]
	v_cvt_pk_fp8_f32 v154, v70, v71 op_sel:[0,0,1]
	v_cvt_pk_fp8_f32 v156, v74, v75 op_sel:[0,0,1]
	v_cvt_pk_fp8_f32 v158, v78, v79 op_sel:[0,0,1]
	v_cvt_pk_fp8_f32 v160, v82, v83 op_sel:[0,0,1]
	v_cvt_pk_fp8_f32 v162, v86, v87 op_sel:[0,0,1]
	v_cvt_pk_fp8_f32 v164, v90, v91 op_sel:[0,0,1]
	v_cvt_pk_fp8_f32 v166, v94, v95 op_sel:[0,0,1]
	v_cvt_pk_fp8_f32 v153, v98, v99 op_sel:[0,0,1]
	v_cvt_pk_fp8_f32 v155, v102, v103 op_sel:[0,0,1]
	v_cvt_pk_fp8_f32 v157, v106, v107 op_sel:[0,0,1]
	v_cvt_pk_fp8_f32 v159, v110, v111 op_sel:[0,0,1]
	v_cvt_pk_fp8_f32 v161, v114, v115 op_sel:[0,0,1]
	v_cvt_pk_fp8_f32 v163, v118, v119 op_sel:[0,0,1]
	v_cvt_pk_fp8_f32 v165, v122, v123 op_sel:[0,0,1]
	v_cvt_pk_fp8_f32 v167, v126, v127 op_sel:[0,0,1]
	s_nop 1
	v_permlane32_swap_b32_e32 v152, v153
	v_permlane32_swap_b32_e32 v154, v155
	v_permlane32_swap_b32_e32 v156, v157
	v_permlane32_swap_b32_e32 v158, v159
	v_permlane32_swap_b32_e32 v160, v161
	v_permlane32_swap_b32_e32 v162, v163
	v_permlane32_swap_b32_e32 v164, v165
	v_permlane32_swap_b32_e32 v166, v167
	global_store_dwordx4 v241, v[152:155], s[10:11] offset:0
	global_store_dwordx4 v241, v[156:159], s[10:11] offset:16
	global_store_dwordx4 v241, v[160:163], s[10:11] offset:32
	global_store_dwordx4 v241, v[164:167], s[10:11] offset:48
	s_add_u32 s12, s12, 1
	s_branch .Latt_unit
